# non-fold weight conversions rewritten by hand as a 3-deep software pipeline (2 tiles in flight, counted vmcnt, double-buffered LDS transpose, one barrier per tile) + attention vmcnt wait fix
# speedup vs baseline: 1.0065x; 1.0065x over previous
; #define LAS __attribute__((address_space(3)))
; __device__ __forceinline__ void tconv_matrix(const float* W, int K, int N, bf16_t* WT, LAS float* scr) { tconv_mat<false>(W, K, N, WT, nullptr, nullptr, nullptr, nullptr, scr); }
; #define AIN(i) (kargs()->in[i])
; template <bool FOLD>
; __device__ __forceinline__ void tconv_mat(const float* W, int K, int N, bf16_t* WT, const float* gam, const float* bet, float* cs, float* bw, LAS float* scr) {
;     const int tkn = K / 64, tnn = N / 64, nt = tkn * tnn, tid = threadIdx.x;
;     const int kk = tid >> 4, n4 = (tid & 15) * 4, n = tid >> 3, k8 = (tid & 7) * 8;
;     int it = blockIdx.x; if (it >= nt) return;
;     f32x4 v0, v1;
;     { const int tk = it / tnn, tn = it % tnn; const float* p = W + (size_t)(tk * 64 + kk) * N + tn * 64 + n4; v0 = __builtin_nontemporal_load((const f32x4*)p); v1 = __builtin_nontemporal_load((const f32x4*)(p + (size_t)32 * N)); }
;     for (;;) {
;         const int tk = it / tnn, tn = it % tnn, nx = it + (int)gridDim.x;
;         const f32x4 w0 = v0, w1 = v1;
;         if (nx < nt) { const int tk2 = nx / tnn, tn2 = nx % tnn; const float* p = W + (size_t)(tk2 * 64 + kk) * N + tn2 * 64 + n4; v0 = __builtin_nontemporal_load((const f32x4*)p); v1 = __builtin_nontemporal_load((const f32x4*)(p + (size_t)32 * N)); }
; __global__ void __launch_bounds__(512, 2) fwd_mega(Args a) {
;     ...
;         tconv_matrix(AIN(3), DM, INW, (bf16_t*)(ws + WS_WIN), (LAS float*)lds);
;         tconv_matrix(AIN(4), DM, DM, (bf16_t*)(ws + WS_WOUT), (LAS float*)lds);
;         tconv_matrix(AIN(15), DFF, DM, (bf16_t*)(ws + WS_WDN), (LAS float*)lds);
.LBB0_10:
	s_or_b64 exec, exec, s[20:21]
	s_load_dwordx2 s[36:37], s[0:1], 0x18
	s_add_u32 s38, s14, 0x200000
	s_addc_u32 s39, s15, 0
	s_movk_i32 s40, 96
	s_movk_i32 s41, 3072
	s_mov_b32 s42, 0x6000
	s_mov_b32 s43, 0x1000
	s_mov_b32 s44, 0x2aaaaab
	s_mov_b32 s45, 0
	s_waitcnt lgkmcnt(0)
	s_branch .LtcA_entry
.LtcA_ret0:
	s_load_dwordx2 s[36:37], s[0:1], 0x20
	s_add_u32 s38, s14, 0x1a00000
	s_addc_u32 s39, s15, 0
	s_movk_i32 s40, 32
	s_movk_i32 s41, 1024
	s_mov_b32 s42, 0x2000
	s_mov_b32 s43, 0x1000
	s_mov_b32 s44, 0x8000000
	s_mov_b32 s45, 1
	s_waitcnt lgkmcnt(0)
	s_branch .LtcA_entry
.LtcA_ret1:
	s_load_dwordx2 s[36:37], s[0:1], 0x78
	s_add_u32 s38, s14, 0x4200000
	s_addc_u32 s39, s15, 0
	s_movk_i32 s40, 32
	s_movk_i32 s41, 4096
	s_mov_b32 s42, 0x2000
	s_mov_b32 s43, 0x4000
	s_mov_b32 s44, 0x8000000
	s_mov_b32 s45, 2
	s_waitcnt lgkmcnt(0)
	s_branch .LtcA_entry
.LtcA_entry:
	v_lshrrev_b32_e32 v88, 4, v241
	v_and_b32_e32 v89, 15, v241
	v_lshlrev_b32_e32 v89, 2, v89
	v_lshrrev_b32_e32 v90, 3, v241
	v_and_b32_e32 v91, 7, v241
	v_lshlrev_b32_e32 v91, 3, v91
	v_mul_lo_u32 v92, v88, s42
	v_lshl_add_u32 v92, v89, 2, v92
	v_mul_u32_u24_e32 v93, 0x104, v89
	v_lshl_add_u32 v93, v88, 2, v93
	v_mul_u32_u24_e32 v94, 0x104, v90
	v_lshl_add_u32 v94, v91, 2, v94
	v_mul_lo_u32 v95, v90, s43
	v_lshl_add_u32 v95, v91, 1, v95
	s_lshl_b32 s46, s42, 5
	s_lshl_b32 s47, s42, 6
	s_lshl_b32 s48, s43, 6
	s_mov_b32 s49, s2
	s_mov_b32 s50, 0
	s_mov_b32 s51, 0
	s_lshl_b32 s58, s16, 1
	s_mul_i32 s60, s16, 3
	s_cmp_lt_u32 s49, s41
	s_cbranch_scc0 .LtcA_done
	s_mov_b32 s52, s49
	s_mul_hi_u32 s54, s52, s44
	s_mul_i32 s55, s54, s40
	s_sub_u32 s55, s52, s55
	s_mul_i32 s56, s54, s47
	s_lshl_b32 s57, s55, 8
	s_add_u32 s56, s56, s57
	v_add_u32_e32 v74, s56, v92
	v_add_u32_e32 v75, s46, v74
	global_load_dwordx4 v[50:53], v74, s[36:37] nt
	global_load_dwordx4 v[54:57], v75, s[36:37] nt
	s_add_u32 s52, s52, s16
	s_cmp_lt_u32 s52, s41
	s_cbranch_scc0 .LtcA_body0
	s_mul_hi_u32 s54, s52, s44
	s_mul_i32 s55, s54, s40
	s_sub_u32 s55, s52, s55
	s_mul_i32 s56, s54, s47
	s_lshl_b32 s57, s55, 8
	s_add_u32 s56, s56, s57
	v_add_u32_e32 v74, s56, v92
	v_add_u32_e32 v75, s46, v74
	global_load_dwordx4 v[58:61], v74, s[36:37] nt
	global_load_dwordx4 v[62:65], v75, s[36:37] nt
	s_add_u32 s52, s52, s16
	s_cmp_lt_u32 s52, s41
	s_cbranch_scc0 .LtcA_body0
	s_mul_hi_u32 s54, s52, s44
	s_mul_i32 s55, s54, s40
	s_sub_u32 s55, s52, s55
	s_mul_i32 s56, s54, s47
	s_lshl_b32 s57, s55, 8
	s_add_u32 s56, s56, s57
	v_add_u32_e32 v74, s56, v92
	v_add_u32_e32 v75, s46, v74
	global_load_dwordx4 v[66:69], v74, s[36:37] nt
	global_load_dwordx4 v[70:73], v75, s[36:37] nt
.LtcA_body0:
	s_add_u32 s59, s49, s58
	s_cmp_lt_u32 s59, s41
	s_cbranch_scc0 .LtcA_w0_0
	s_cmp_eq_u32 s50, 0
	s_cbranch_scc1 .LtcA_w4_0
	s_cmp_eq_u32 s50, 1
	s_cbranch_scc1 .LtcA_w5_0
	s_cmp_eq_u32 s50, 2
	s_cbranch_scc1 .LtcA_w6_0
	s_waitcnt vmcnt(7)
	s_branch .LtcA_wd_0
.LtcA_w6_0:
	s_waitcnt vmcnt(6)
	s_branch .LtcA_wd_0
.LtcA_w5_0:
	s_waitcnt vmcnt(5)
	s_branch .LtcA_wd_0
.LtcA_w4_0:
	s_waitcnt vmcnt(4)
	s_branch .LtcA_wd_0

; __device__ __forceinline__ unsigned pk2(float lo, float hi) { return pg8::cvt_pk_bf16(lo, hi); }
; template <bool FOLD>
; __device__ __forceinline__ void tconv_mat(const float* W, int K, int N, bf16_t* WT, const float* gam, const float* bet, float* cs, float* bw, LAS float* scr) {
;     ...
;         if (nx < nt) { const int tk2 = nx / tnn, tn2 = nx % tnn; const float* p = W + (size_t)(tk2 * 64 + kk) * N + tn2 * 64 + n4; v0 = __builtin_nontemporal_load((const f32x4*)p); v1 = __builtin_nontemporal_load((const f32x4*)(p + (size_t)32 * N)); }
;         scr[(n4 + 0) * 65 + kk] = w0[0]; scr[(n4 + 1) * 65 + kk] = w0[1]; scr[(n4 + 2) * 65 + kk] = w0[2]; scr[(n4 + 3) * 65 + kk] = w0[3];
;         scr[(n4 + 0) * 65 + kk + 32] = w1[0]; scr[(n4 + 1) * 65 + kk + 32] = w1[1]; scr[(n4 + 2) * 65 + kk + 32] = w1[2]; scr[(n4 + 3) * 65 + kk + 32] = w1[3];
;         __syncthreads();
;         { float x[8]; float bsum = 0.f, csum = 0.f;
;           if (FOLD) { const f32x4 g0 = *(const f32x4*)(gam + tk * 64 + k8), g1 = *(const f32x4*)(gam + tk * 64 + k8 + 4), b0 = *(const f32x4*)(bet + tk * 64 + k8), b1 = *(const f32x4*)(bet + tk * 64 + k8 + 4);
; #pragma unroll
;               for (int j = 0; j < 8; ++j) { const float xv = scr[n * 65 + k8 + j]; bsum += xv * (j < 4 ? b0[j & 3] : b1[j & 3]); x[j] = xv * (j < 4 ? g0[j & 3] : g1[j & 3]); }
;           } else {
; #pragma unroll
;               for (int j = 0; j < 8; ++j) x[j] = scr[n * 65 + k8 + j]; }
;           u32x4 w; w.x = pk2(x[0], x[1]); w.y = pk2(x[2], x[3]); w.z = pk2(x[4], x[5]); w.w = pk2(x[6], x[7]);
;           *(u32x4*)(WT + (size_t)(tn * 64 + n) * K + tk * 64 + k8) = w;
;           if (FOLD) {
; #pragma unroll
;               for (int c = 0; c < 4; ++c) csum += __uint_as_float(w[c] << 16) + __uint_as_float(w[c] & 0xffff0000u);
;               csum += __shfl_xor(csum, 1); bsum += __shfl_xor(bsum, 1); csum += __shfl_xor(csum, 2); bsum += __shfl_xor(bsum, 2); csum += __shfl_xor(csum, 4); bsum += __shfl_xor(bsum, 4);
;               if ((tid & 7) == 0) { __hip_atomic_fetch_add(cs + tn * 64 + n, csum, __ATOMIC_RELAXED, __HIP_MEMORY_SCOPE_AGENT); __hip_atomic_fetch_add(bw + tn * 64 + n, bsum, __ATOMIC_RELAXED, __HIP_MEMORY_SCOPE_AGENT); } } }
;         __syncthreads();
;         if (nx >= nt) break;
;         it = nx;
.LtcA_wd_0:
	v_add_u32_e32 v76, s51, v93
	ds_write2_b32 v76, v50, v54 offset1:32
	ds_write2_b32 v76, v51, v55 offset0:65 offset1:97
	ds_write2_b32 v76, v52, v56 offset0:130 offset1:162
	ds_write2_b32 v76, v53, v57 offset0:195 offset1:227
	s_waitcnt lgkmcnt(0)
	s_barrier
	s_add_u32 s52, s49, s60
	s_cmp_lt_u32 s52, s41
	s_cbranch_scc0 .LtcA_nl_0
	s_mul_hi_u32 s54, s52, s44
	s_mul_i32 s55, s54, s40
	s_sub_u32 s55, s52, s55
	s_mul_i32 s56, s54, s47
	s_lshl_b32 s57, s55, 8
	s_add_u32 s56, s56, s57
	v_add_u32_e32 v74, s56, v92
	v_add_u32_e32 v75, s46, v74
	global_load_dwordx4 v[50:53], v74, s[36:37] nt
	global_load_dwordx4 v[54:57], v75, s[36:37] nt
.LtcA_nl_0:
	v_add_u32_e32 v77, s51, v94
	ds_read2_b32 v[80:81], v77 offset1:1
	ds_read2_b32 v[82:83], v77 offset0:2 offset1:3
	ds_read2_b32 v[84:85], v77 offset0:4 offset1:5
	ds_read2_b32 v[86:87], v77 offset0:6 offset1:7
	s_mul_hi_u32 s54, s49, s44
	s_mul_i32 s55, s54, s40
	s_sub_u32 s55, s49, s55
	s_mul_i32 s56, s55, s48
	s_lshl_b32 s57, s54, 7
	s_add_u32 s56, s56, s57
	v_add_u32_e32 v78, s56, v95
	s_waitcnt lgkmcnt(0)
	v_cvt_pk_bf16_f32 v80, v80, v81
	v_cvt_pk_bf16_f32 v81, v82, v83
	v_cvt_pk_bf16_f32 v82, v84, v85
	v_cvt_pk_bf16_f32 v83, v86, v87
	global_store_dwordx4 v78, v[80:83], s[38:39]
	s_sub_u32 s51, 0x4100, s51
	s_add_u32 s49, s49, s16
	s_add_u32 s50, s50, 1
	s_cmp_lt_u32 s49, s41
	s_cbranch_scc0 .LtcA_done

; template <bool FOLD>
; __device__ __forceinline__ void tconv_mat(const float* W, int K, int N, bf16_t* WT, const float* gam, const float* bet, float* cs, float* bw, LAS float* scr) {
;     ...
;         if (nx < nt) { const int tk2 = nx / tnn, tn2 = nx % tnn; const float* p = W + (size_t)(tk2 * 64 + kk) * N + tn2 * 64 + n4; v0 = __builtin_nontemporal_load((const f32x4*)p); v1 = __builtin_nontemporal_load((const f32x4*)(p + (size_t)32 * N)); }
;         scr[(n4 + 0) * 65 + kk] = w0[0]; scr[(n4 + 1) * 65 + kk] = w0[1]; scr[(n4 + 2) * 65 + kk] = w0[2]; scr[(n4 + 3) * 65 + kk] = w0[3];
;         scr[(n4 + 0) * 65 + kk + 32] = w1[0]; scr[(n4 + 1) * 65 + kk + 32] = w1[1]; scr[(n4 + 2) * 65 + kk + 32] = w1[2]; scr[(n4 + 3) * 65 + kk + 32] = w1[3];
;         __syncthreads();
.LtcA_wd_1:
	v_add_u32_e32 v76, s51, v93
	ds_write2_b32 v76, v58, v62 offset1:32
	ds_write2_b32 v76, v59, v63 offset0:65 offset1:97
	ds_write2_b32 v76, v60, v64 offset0:130 offset1:162
	ds_write2_b32 v76, v61, v65 offset0:195 offset1:227
	s_waitcnt lgkmcnt(0)
	s_barrier
	s_add_u32 s52, s49, s60
	s_cmp_lt_u32 s52, s41
	s_cbranch_scc0 .LtcA_nl_1
	s_mul_hi_u32 s54, s52, s44
	s_mul_i32 s55, s54, s40
	s_sub_u32 s55, s52, s55
	s_mul_i32 s56, s54, s47
	s_lshl_b32 s57, s55, 8
	s_add_u32 s56, s56, s57
	v_add_u32_e32 v74, s56, v92
	v_add_u32_e32 v75, s46, v74
	global_load_dwordx4 v[58:61], v74, s[36:37] nt
	global_load_dwordx4 v[62:65], v75, s[36:37] nt

; __device__ __forceinline__ unsigned pk2(float lo, float hi) { return pg8::cvt_pk_bf16(lo, hi); }
; template <bool FOLD>
; __device__ __forceinline__ void tconv_mat(const float* W, int K, int N, bf16_t* WT, const float* gam, const float* bet, float* cs, float* bw, LAS float* scr) {
;     ...
;         scr[(n4 + 0) * 65 + kk] = w0[0]; scr[(n4 + 1) * 65 + kk] = w0[1]; scr[(n4 + 2) * 65 + kk] = w0[2]; scr[(n4 + 3) * 65 + kk] = w0[3];
;         scr[(n4 + 0) * 65 + kk + 32] = w1[0]; scr[(n4 + 1) * 65 + kk + 32] = w1[1]; scr[(n4 + 2) * 65 + kk + 32] = w1[2]; scr[(n4 + 3) * 65 + kk + 32] = w1[3];
;         __syncthreads();
;         { float x[8]; float bsum = 0.f, csum = 0.f;
;           if (FOLD) { const f32x4 g0 = *(const f32x4*)(gam + tk * 64 + k8), g1 = *(const f32x4*)(gam + tk * 64 + k8 + 4), b0 = *(const f32x4*)(bet + tk * 64 + k8), b1 = *(const f32x4*)(bet + tk * 64 + k8 + 4);
; #pragma unroll
;               for (int j = 0; j < 8; ++j) { const float xv = scr[n * 65 + k8 + j]; bsum += xv * (j < 4 ? b0[j & 3] : b1[j & 3]); x[j] = xv * (j < 4 ? g0[j & 3] : g1[j & 3]); }
;           } else {
; #pragma unroll
;               for (int j = 0; j < 8; ++j) x[j] = scr[n * 65 + k8 + j]; }
;           u32x4 w; w.x = pk2(x[0], x[1]); w.y = pk2(x[2], x[3]); w.z = pk2(x[4], x[5]); w.w = pk2(x[6], x[7]);
;           *(u32x4*)(WT + (size_t)(tn * 64 + n) * K + tk * 64 + k8) = w;
;           if (FOLD) {
; #pragma unroll
;               for (int c = 0; c < 4; ++c) csum += __uint_as_float(w[c] << 16) + __uint_as_float(w[c] & 0xffff0000u);
;               csum += __shfl_xor(csum, 1); bsum += __shfl_xor(bsum, 1); csum += __shfl_xor(csum, 2); bsum += __shfl_xor(bsum, 2); csum += __shfl_xor(csum, 4); bsum += __shfl_xor(bsum, 4);
;               if ((tid & 7) == 0) { __hip_atomic_fetch_add(cs + tn * 64 + n, csum, __ATOMIC_RELAXED, __HIP_MEMORY_SCOPE_AGENT); __hip_atomic_fetch_add(bw + tn * 64 + n, bsum, __ATOMIC_RELAXED, __HIP_MEMORY_SCOPE_AGENT); } } }
;         __syncthreads();
;         if (nx >= nt) break;
;         it = nx;
;     }
; }
.LtcA_wd_2:
	v_add_u32_e32 v76, s51, v93
	ds_write2_b32 v76, v66, v70 offset1:32
	ds_write2_b32 v76, v67, v71 offset0:65 offset1:97
	ds_write2_b32 v76, v68, v72 offset0:130 offset1:162
	ds_write2_b32 v76, v69, v73 offset0:195 offset1:227
	s_waitcnt lgkmcnt(0)
	s_barrier
	s_add_u32 s52, s49, s60
	s_cmp_lt_u32 s52, s41
	s_cbranch_scc0 .LtcA_nl_2
	s_mul_hi_u32 s54, s52, s44
	s_mul_i32 s55, s54, s40
	s_sub_u32 s55, s52, s55
	s_mul_i32 s56, s54, s47
	s_lshl_b32 s57, s55, 8
	s_add_u32 s56, s56, s57
	v_add_u32_e32 v74, s56, v92
	v_add_u32_e32 v75, s46, v74
	global_load_dwordx4 v[66:69], v74, s[36:37] nt
	global_load_dwordx4 v[70:73], v75, s[36:37] nt
.LtcA_nl_2:
	v_add_u32_e32 v77, s51, v94
	ds_read2_b32 v[80:81], v77 offset1:1
	ds_read2_b32 v[82:83], v77 offset0:2 offset1:3
	ds_read2_b32 v[84:85], v77 offset0:4 offset1:5
	ds_read2_b32 v[86:87], v77 offset0:6 offset1:7
	s_mul_hi_u32 s54, s49, s44
	s_mul_i32 s55, s54, s40
	s_sub_u32 s55, s49, s55
	s_mul_i32 s56, s55, s48
	s_lshl_b32 s57, s54, 7
	s_add_u32 s56, s56, s57
	v_add_u32_e32 v78, s56, v95
	s_waitcnt lgkmcnt(0)
	v_cvt_pk_bf16_f32 v80, v80, v81
	v_cvt_pk_bf16_f32 v81, v82, v83
	v_cvt_pk_bf16_f32 v82, v84, v85
	v_cvt_pk_bf16_f32 v83, v86, v87
	global_store_dwordx4 v78, v[80:83], s[38:39]
	s_sub_u32 s51, 0x4100, s51
	s_add_u32 s49, s49, s16
	s_add_u32 s50, s50, 1
	s_cmp_lt_u32 s49, s41
	s_cbranch_scc0 .LtcA_done
	s_branch .LtcA_body0
.LtcA_done:
	s_barrier
	s_cmp_eq_u32 s45, 0
	s_cbranch_scc1 .LtcA_ret0
	s_cmp_eq_u32 s45, 1
	s_cbranch_scc1 .LtcA_ret1
	s_branch .LtcA_ret2
.LtcA_ret2:
.LBB0_31:
	v_lshl_add_u32 v2, s2, 9, v241
	s_mov_b32 s4, 0x18000
	v_cmp_gt_i32_e32 vcc, s4, v2
	s_and_saveexec_b64 s[4:5], vcc
	s_cbranch_execz .LBB0_34
	s_add_u32 s6, s14, 0x20000
	s_addc_u32 s7, s15, 0
	s_lshl_b32 s22, s16, 9
	s_mov_b64 s[20:21], 0
	v_mov_b32_e32 v1, 0
	s_mov_b32 s23, 0x17fff
	v_mov_b32_e32 v4, v2

; #define LAS __attribute__((address_space(3)))
; __device__ __forceinline__ void tconv_matrix(const float* W, int K, int N, bf16_t* WT, LAS float* scr) { tconv_mat<false>(W, K, N, WT, nullptr, nullptr, nullptr, nullptr, scr); }
; __device__ __forceinline__ void tconv_matrix_fold(const float* W, int K, int N, bf16_t* WT, const float* gam, const float* bet, float* cs, float* bw, LAS float* scr) { tconv_mat<true>(W, K, N, WT, gam, bet, cs, bw, scr); }
; #define AIN(i) (kargs()->in[i])
; #define CSUP(l) FOLDV(l, 0)
; #define BWUP(l) FOLDV(l, 8192)
; template <bool FOLD>
; __device__ __forceinline__ void tconv_mat(const float* W, int K, int N, bf16_t* WT, const float* gam, const float* bet, float* cs, float* bw, LAS float* scr) {
;     const int tkn = K / 64, tnn = N / 64, nt = tkn * tnn, tid = threadIdx.x;
;     const int kk = tid >> 4, n4 = (tid & 15) * 4, n = tid >> 3, k8 = (tid & 7) * 8;
;     int it = blockIdx.x; if (it >= nt) return;
;     f32x4 v0, v1;
;     { const int tk = it / tnn, tn = it % tnn; const float* p = W + (size_t)(tk * 64 + kk) * N + tn * 64 + n4; v0 = __builtin_nontemporal_load((const f32x4*)p); v1 = __builtin_nontemporal_load((const f32x4*)(p + (size_t)32 * N)); }
;     for (;;) {
;         const int tk = it / tnn, tn = it % tnn, nx = it + (int)gridDim.x;
;         const f32x4 w0 = v0, w1 = v1;
;         if (nx < nt) { const int tk2 = nx / tnn, tn2 = nx % tnn; const float* p = W + (size_t)(tk2 * 64 + kk) * N + tn2 * 64 + n4; v0 = __builtin_nontemporal_load((const f32x4*)p); v1 = __builtin_nontemporal_load((const f32x4*)(p + (size_t)32 * N)); }
; __global__ void __launch_bounds__(512, 2) fwd_mega(Args a) {
;     ...
;             tconv_matrix(AIN(4) + (size_t)DM * DM, DM, DM, (bf16_t*)(ws + WS_WOUT), (LAS float*)lds);
;             tconv_matrix_fold(AIN(14) + (size_t)DM * DFF, DM, DFF, (bf16_t*)(ws + WS_WUP), AIN(12) + DM, AIN(13) + DM, CSUP(1), BWUP(1), (LAS float*)lds);
;             tconv_matrix(AIN(15) + (size_t)DFF * DM, DFF, DM, (bf16_t*)(ws + WS_WDN), (LAS float*)lds);
.LBB0_594:
	s_load_dwordx2 s[36:37], s[0:1], 0x20
	s_add_u32 s38, s14, 0x1a00000
	s_addc_u32 s39, s15, 0
	s_movk_i32 s40, 32
	s_movk_i32 s41, 1024
	s_mov_b32 s42, 0x2000
	s_mov_b32 s43, 0x1000
	s_mov_b32 s44, 0x8000000
	s_mov_b32 s45, 0
	s_waitcnt lgkmcnt(0)
	s_add_u32 s36, s36, 0x1000000
	s_addc_u32 s37, s37, 0
	s_branch .LtcB_entry
.LtcB_ret0:
.LBB0_601:
	s_cmpk_lt_i32 s2, 0x1000
	s_mov_b64 s[12:13], s[0:1]
	s_mov_b64 s[4:5], s[0:1]
	s_waitcnt lgkmcnt(0)
	s_mov_b64 s[30:31], s[0:1]
	s_cselect_b64 s[10:11], -1, 0
	s_cmpk_gt_i32 s2, 0xfff
	s_cbranch_scc1 .LBB0_608
	s_load_dwordx2 s[12:13], s[12:13], 0x70
	v_lshlrev_b32_e32 v0, 2, v241
	v_and_b32_e32 v0, 60, v0
	v_mov_b32_e32 v19, 0
	v_lshlrev_b32_e32 v18, 2, v0
	s_waitcnt lgkmcnt(0)
	s_add_u32 s12, s12, 0x4000000
	s_addc_u32 s13, s13, 0
	s_add_u32 s28, s14, 0x2200000
	s_addc_u32 s29, s15, 0
	s_ashr_i32 s34, s2, 31
	s_lshr_b32 s34, s34, 25
	s_add_i32 s34, s2, s34
	s_ashr_i32 s35, s34, 7
	s_and_b32 s34, s34, 0x3ffff80
	v_lshl_or_b32 v2, s35, 6, v32
	s_sub_i32 s34, s2, s34
	v_ashrrev_i32_e32 v3, 31, v2
	v_lshlrev_b64 v[2:3], 15, v[2:3]
	s_lshl_b32 s34, s34, 6
	v_lshl_add_u64 v[2:3], s[12:13], 0, v[2:3]
	s_ashr_i32 s35, s34, 31
	v_lshl_add_u64 v[2:3], s[34:35], 2, v[2:3]
	v_lshl_add_u64 v[2:3], v[2:3], 0, v[18:19]
	s_mov_b32 s34, 0x100000
	v_add_co_u32_e32 v4, vcc, s34, v2
	v_mbcnt_lo_u32_b32 v1, -1, 0
	s_nop 0
	v_addc_co_u32_e32 v5, vcc, 0, v3, vcc
	global_load_dwordx4 v[8:11], v[4:5], off nt
	global_load_dwordx4 v[12:15], v[2:3], off nt
	v_mbcnt_hi_u32_b32 v1, -1, v1
	v_mov_b32_e32 v17, v19
	v_and_b32_e32 v18, 64, v1
	s_load_dwordx2 s[38:39], s[4:5], 0x60
	s_load_dwordx2 s[40:41], s[30:31], 0x68
	v_mul_u32_u24_e32 v6, 0x104, v0
	v_xor_b32_e32 v7, 1, v1
	v_lshl_add_u64 v[4:5], s[14:15], 0, v[16:17]
	v_lshlrev_b32_e32 v16, 2, v0
	v_add_u32_e32 v0, 64, v18
	s_mov_b64 s[36:37], 0x1a4000
	s_mov_b64 s[42:43], 0x19c000
	v_xor_b32_e32 v24, 2, v1
	v_cmp_lt_i32_e32 vcc, v7, v0
	v_xor_b32_e32 v25, 4, v1
	v_lshl_add_u64 v[20:21], v[4:5], 0, s[36:37]
	v_lshl_add_u64 v[22:23], v[4:5], 0, s[42:43]
	v_cndmask_b32_e32 v4, v1, v7, vcc
	v_cmp_lt_i32_e32 vcc, v24, v0
	v_lshlrev_b32_e32 v18, 5, v35
	v_lshlrev_b32_e32 v2, 3, v35
	v_cndmask_b32_e32 v5, v1, v24, vcc
	v_cmp_lt_i32_e32 vcc, v25, v0
	s_mov_b64 s[30:31], 0x2000
	v_mul_u32_u24_e32 v3, 0x104, v33
	v_cndmask_b32_e32 v0, v1, v25, vcc
	v_lshlrev_b32_e32 v30, 2, v4
	v_lshlrev_b32_e32 v31, 2, v5
	v_lshlrev_b32_e32 v36, 2, v0
	s_waitcnt lgkmcnt(0)
	v_lshl_add_u64 v[0:1], s[38:39], 0, v[18:19]
	v_lshl_add_u64 v[4:5], s[40:41], 0, v[18:19]
	v_cmp_eq_u32_e64 s[4:5], 0, v35
	v_add3_u32 v29, 0, v6, v34
	v_add3_u32 v35, 0, v3, v18
	v_lshlrev_b32_e32 v18, 1, v2
	v_lshl_add_u64 v[24:25], v[0:1], 0, s[30:31]
	v_lshl_add_u64 v[26:27], v[4:5], 0, s[30:31]
	s_mov_b32 s34, s2
	s_lshl_b32 s36, s2, 6
	s_lshl_b32 s37, s16, 6
	s_waitcnt vmcnt(0)
	v_mov_b64_e32 v[4:5], v[8:9]
	v_mov_b64_e32 v[0:1], v[12:13]
	v_mov_b64_e32 v[6:7], v[10:11]
	v_mov_b64_e32 v[2:3], v[14:15]
	s_branch .LBB0_604

; #define LAS __attribute__((address_space(3)))
; __device__ __forceinline__ void tconv_matrix(const float* W, int K, int N, bf16_t* WT, LAS float* scr) { tconv_mat<false>(W, K, N, WT, nullptr, nullptr, nullptr, nullptr, scr); }
; #define AIN(i) (kargs()->in[i])
; __global__ void __launch_bounds__(512, 2) fwd_mega(Args a) {
;     ...
;             tconv_matrix(AIN(15) + (size_t)DFF * DM, DFF, DM, (bf16_t*)(ws + WS_WDN), (LAS float*)lds);
.LBB0_608:
	s_load_dwordx2 s[36:37], s[0:1], 0x78
	s_add_u32 s38, s14, 0x4200000
	s_addc_u32 s39, s15, 0
	s_movk_i32 s40, 32
	s_movk_i32 s41, 4096
	s_mov_b32 s42, 0x2000
	s_mov_b32 s43, 0x4000
	s_mov_b32 s44, 0x8000000
	s_mov_b32 s45, 1
	s_waitcnt lgkmcnt(0)
	s_add_u32 s36, s36, 0x4000000
	s_addc_u32 s37, s37, 0
	s_branch .LtcB_entry

; #define LAS __attribute__((address_space(3)))
; __device__ __forceinline__ unsigned xb_ld(unsigned* p)              { return __hip_atomic_load(p, __ATOMIC_RELAXED, __HIP_MEMORY_SCOPE_AGENT); }
; __device__ __forceinline__ unsigned xb_xcc_id() { return (unsigned)__builtin_amdgcn_s_getreg((3 << 11) | 20) & 0xFu; }
; __device__ __forceinline__ void xcd_barrier_complete(unsigned* bar, unsigned x, unsigned& nloc, unsigned& nx) {
;     const unsigned G = gridDim.x * gridDim.y * gridDim.z;
;     unsigned sum, cnt, mine, sp = 0u;
;     for (;;) {
;         sum = 0u; cnt = 0u; mine = 0u;
; #pragma unroll
;         for (unsigned j = 0; j < 16; ++j) { const unsigned c = xb_ld(&bar[XB_XCNT(j)]); sum += c; cnt += (c > 0u) ? 1u : 0u; mine = (j == x) ? c : mine; }
;         if (sum == G) break;
; __device__ __forceinline__ void xcd_barrier(unsigned* bar, volatile LAS unsigned* st) {
;     asm volatile("s_waitcnt vmcnt(0)" ::: "memory");
;     __syncthreads();
;     if (threadIdx.x == 0) {
;         __builtin_amdgcn_s_waitcnt(0);
;         const unsigned x = xb_xcc_id();
;         unsigned nloc = st[0], nx = st[1];
;         if (nloc == 0u) { xcd_barrier_complete(bar, x, nloc, nx); st[0] = nloc; st[1] = nx; }
.LtcB_done:
	s_barrier
	s_cmp_eq_u32 s45, 0
	s_cbranch_scc1 .LtcB_ret0
	s_branch .LtcB_ret1
.LtcB_ret1:
.LBB0_615:
	s_cmp_gt_i32 s66, 7
	s_cselect_b64 s[4:5], -1, 0
	s_and_b64 s[6:7], s[6:7], s[4:5]
	s_andn2_b64 vcc, exec, s[6:7]
	s_cbranch_vccnz .LBB0_669
	s_waitcnt vmcnt(0)
	s_waitcnt vmcnt(0) lgkmcnt(0)
	s_barrier
	s_and_saveexec_b64 s[6:7], s[8:9]
	s_cbranch_execz .LBB0_668
	s_add_i32 s11, 0, 0x20600
	v_mov_b32_e32 v0, s11
	s_waitcnt vmcnt(0) expcnt(0) lgkmcnt(0)
	s_getreg_b32 s10, hwreg(HW_REG_XCC_ID, 0, 4)
	ds_read_b32 v2, v0
	s_add_i32 s11, 0, 0x20604
	v_mov_b32_e32 v0, s11
	ds_read_b32 v0, v0
	s_and_b32 s67, s10, 15
	s_waitcnt lgkmcnt(1)
	v_cmp_ne_u32_e32 vcc, 0, v2
	s_cbranch_vccnz .LBB0_632
	s_add_u32 s10, s14, 0x100200
	s_addc_u32 s11, s15, 0
	s_add_u32 s12, s14, 0x100400
	s_addc_u32 s13, s15, 0
	s_add_u32 s28, s14, 0x100500
	s_addc_u32 s29, s15, 0
	s_add_u32 s30, s14, 0x100600
	s_addc_u32 s31, s15, 0
	s_add_u32 s34, s14, 0x100700
	s_addc_u32 s35, s15, 0
	s_add_u32 s36, s14, 0x100800
	s_addc_u32 s37, s15, 0
	s_add_u32 s38, s14, 0x100900
	s_addc_u32 s39, s15, 0
	s_add_u32 s40, s14, 0x100a00
	s_addc_u32 s41, s15, 0
	s_add_u32 s42, s14, 0x100b00
	s_addc_u32 s43, s15, 0
	s_add_u32 s44, s14, 0x100c00
	s_addc_u32 s45, s15, 0
	s_add_u32 s46, s14, 0x100d00
	s_addc_u32 s47, s15, 0
	s_add_u32 s48, s14, 0x100e00
	s_addc_u32 s49, s15, 0
	s_add_u32 s50, s14, 0x100f00
	s_addc_u32 s51, s15, 0
	s_add_u32 s52, s14, 0x101000
	s_addc_u32 s53, s15, 0
	s_add_u32 s54, s14, 0x101100
	s_addc_u32 s55, s15, 0
	s_add_u32 s56, s14, 0x101200
	s_addc_u32 s57, s15, 0
	s_mul_i32 s68, s17, s33
	s_add_u32 s58, s14, 0x101300
	s_mul_i32 s68, s68, s16
	s_addc_u32 s59, s15, 0
	s_mov_b32 s69, 1
	v_mov_b32_e32 v16, 0
	s_branch .LBB0_620
